# swiglu: older wave half starts its epilogue one interval early; alignment barrier moved to the middle of the epilogue
# baseline (speedup 1.0000x reference)
.Lpeel_exit_swiglu:
.LBB0_531:
	v_lshl_add_u32 v154, s54, 12, v145
	ds_read_b128 v[96:99], v154
	ds_read_b128 v[234:237], v154 offset:256
	s_waitcnt lgkmcnt(1)
	v_mov_b32_e32 v150, v97
	v_mov_b32_e32 v151, v98
	v_mov_b32_e32 v97, v99
	v_pk_add_f32 v[96:97], v[150:151], v[96:97]
	v_lshl_add_u32 v151, s24, 8, v139
	v_add_f32_e32 v96, v96, v97
	v_fmamk_f32 v96, v96, 0x3a800000, v229
	v_rsq_f32_e32 v150, v96
	ds_read_b128 v[96:99], v154 offset:512
	v_pk_mul_f32 v[128:129], v[128:129], v[150:151] op_sel_hi:[1,0]
	v_pk_mul_f32 v[124:125], v[124:125], v[150:151] op_sel_hi:[1,0]
	s_waitcnt lgkmcnt(1)
	v_mov_b32_e32 v152, v235
	v_mov_b32_e32 v153, v236
	v_mov_b32_e32 v235, v237
	v_pk_add_f32 v[234:235], v[152:153], v[234:235]
	v_pk_mul_f32 v[124:125], v[124:125], v[128:129]
	v_add_f32_e32 v234, v234, v235
	v_fmamk_f32 v234, v234, 0x3a800000, v229
	v_rsq_f32_e32 v148, v234
	ds_read_b128 v[234:237], v154 offset:768
	v_pk_mul_f32 v[128:129], v[128:129], s[68:69] op_sel_hi:[1,0]
	v_pk_mul_f32 v[126:127], v[126:127], v[150:151] op_sel_hi:[1,0]
	v_exp_f32_e32 v128, v128
	v_exp_f32_e32 v129, v129
	s_waitcnt lgkmcnt(1)
	v_mov_b32_e32 v152, v97
	v_mov_b32_e32 v153, v98
	v_mov_b32_e32 v97, v99
	v_pk_add_f32 v[96:97], v[152:153], v[96:97]
	v_pk_add_f32 v[128:129], v[128:129], 1.0 op_sel_hi:[1,0]
	v_add_f32_e32 v96, v96, v97
	v_fmamk_f32 v96, v96, 0x3a800000, v229
	v_rsq_f32_e32 v146, v96
	ds_read_b128 v[96:99], v154 offset:2048
	v_rcp_f32_e32 v128, v128
	v_rcp_f32_e32 v129, v129
	v_pk_mul_f32 v[120:121], v[120:121], v[150:151] op_sel_hi:[1,0]
	v_pk_mul_f32 v[116:117], v[116:117], v[150:151] op_sel_hi:[1,0]
	s_waitcnt lgkmcnt(1)
	v_mov_b32_e32 v152, v235
	v_mov_b32_e32 v153, v236
	v_mov_b32_e32 v235, v237
	v_pk_add_f32 v[234:235], v[152:153], v[234:235]
	v_pk_mul_f32 v[124:125], v[124:125], v[128:129]
	v_add_f32_e32 v234, v234, v235
	v_fmamk_f32 v234, v234, 0x3a800000, v229
	v_rsq_f32_e32 v144, v234
	ds_read_b128 v[234:237], v154 offset:2304
	v_pk_mul_f32 v[128:129], v[130:131], v[150:151] op_sel_hi:[1,0]
	v_pk_mul_f32 v[116:117], v[120:121], v[116:117]
	v_pk_mul_f32 v[126:127], v[128:129], v[126:127]
	v_pk_mul_f32 v[128:129], v[128:129], s[68:69] op_sel_hi:[1,0]
	s_waitcnt lgkmcnt(1)
	v_mov_b32_e32 v152, v97
	v_mov_b32_e32 v153, v98
	v_mov_b32_e32 v97, v99
	v_pk_add_f32 v[96:97], v[152:153], v[96:97]
	v_pk_mul_f32 v[120:121], v[120:121], s[68:69] op_sel_hi:[1,0]
	v_add_f32_e32 v96, v96, v97
	v_fmamk_f32 v96, v96, 0x3a800000, v229
	v_rsq_f32_e32 v142, v96
	ds_read_b128 v[96:99], v154 offset:2560
	v_exp_f32_e32 v128, v128
	v_exp_f32_e32 v129, v129
	v_exp_f32_e32 v120, v120
	v_exp_f32_e32 v121, v121
	s_waitcnt lgkmcnt(1)
	v_mov_b32_e32 v152, v235
	v_mov_b32_e32 v153, v236
	v_mov_b32_e32 v235, v237
	v_pk_add_f32 v[234:235], v[152:153], v[234:235]
	v_pk_mul_f32 v[112:113], v[112:113], v[148:149] op_sel_hi:[1,0]
	v_add_f32_e32 v234, v234, v235
	v_fmamk_f32 v234, v234, 0x3a800000, v229
	v_rsq_f32_e32 v140, v234
	ds_read_b128 v[234:237], v154 offset:2816
	v_pk_mul_f32 v[108:109], v[108:109], v[148:149] op_sel_hi:[1,0]
	v_pk_add_f32 v[128:129], v[128:129], 1.0 op_sel_hi:[1,0]
	v_pk_mul_f32 v[108:109], v[108:109], v[112:113]
	v_pk_mul_f32 v[112:113], v[112:113], s[68:69] op_sel_hi:[1,0]
	v_pk_add_f32 v[120:121], v[120:121], 1.0 op_sel_hi:[1,0]
	v_exp_f32_e32 v112, v112
	v_exp_f32_e32 v113, v113
	v_rcp_f32_e32 v128, v128
	v_rcp_f32_e32 v129, v129
	v_rcp_f32_e32 v120, v120
	v_rcp_f32_e32 v121, v121
	s_waitcnt lgkmcnt(1)
	v_mov_b32_e32 v152, v97
	v_mov_b32_e32 v153, v98
	v_mov_b32_e32 v97, v99
	v_pk_add_f32 v[96:97], v[152:153], v[96:97]
	v_pk_add_f32 v[112:113], v[112:113], 1.0 op_sel_hi:[1,0]
	v_add_f32_e32 v96, v96, v97
	v_fmamk_f32 v96, v96, 0x3a800000, v229
	v_pk_mul_f32 v[126:127], v[126:127], v[128:129]
	v_pk_mul_f32 v[116:117], v[116:117], v[120:121]
	v_rcp_f32_e32 v112, v112
	v_rcp_f32_e32 v113, v113
	v_rsq_f32_e32 v138, v96
	v_cvt_pk_bf16_f32 v124, v124, v125
	v_cvt_pk_bf16_f32 v125, v126, v127
	v_cvt_pk_bf16_f32 v126, v116, v117
	v_pk_mul_f32 v[116:117], v[122:123], v[150:151] op_sel_hi:[1,0]
	v_pk_mul_f32 v[118:119], v[118:119], v[150:151] op_sel_hi:[1,0]
	v_pk_mul_f32 v[108:109], v[108:109], v[112:113]
	v_pk_mul_f32 v[118:119], v[116:117], v[118:119]
	v_pk_mul_f32 v[116:117], v[116:117], s[68:69] op_sel_hi:[1,0]
	v_pk_mul_f32 v[112:113], v[114:115], v[148:149] op_sel_hi:[1,0]
	v_exp_f32_e32 v116, v116
	v_exp_f32_e32 v117, v117
	v_pk_mul_f32 v[110:111], v[110:111], v[148:149] op_sel_hi:[1,0]
	v_pk_mul_f32 v[104:105], v[104:105], v[148:149] op_sel_hi:[1,0]
	v_pk_mul_f32 v[100:101], v[100:101], v[148:149] op_sel_hi:[1,0]
	v_pk_mul_f32 v[110:111], v[112:113], v[110:111]
	v_pk_mul_f32 v[112:113], v[112:113], s[68:69] op_sel_hi:[1,0]
	v_pk_mul_f32 v[100:101], v[104:105], v[100:101]
	v_pk_mul_f32 v[104:105], v[104:105], s[68:69] op_sel_hi:[1,0]
	v_exp_f32_e32 v112, v112
	v_exp_f32_e32 v113, v113
	v_exp_f32_e32 v104, v104
	v_exp_f32_e32 v105, v105
	v_pk_add_f32 v[116:117], v[116:117], 1.0 op_sel_hi:[1,0]
	v_pk_mul_f32 v[92:93], v[92:93], v[146:147] op_sel_hi:[1,0]
	v_rcp_f32_e32 v116, v116
	v_rcp_f32_e32 v117, v117
	v_pk_mul_f32 v[88:89], v[88:89], v[146:147] op_sel_hi:[1,0]
	v_pk_add_f32 v[112:113], v[112:113], 1.0 op_sel_hi:[1,0]
	v_pk_mul_f32 v[88:89], v[88:89], v[92:93]
	v_pk_mul_f32 v[92:93], v[92:93], s[68:69] op_sel_hi:[1,0]
	v_pk_add_f32 v[104:105], v[104:105], 1.0 op_sel_hi:[1,0]
	v_exp_f32_e32 v92, v92
	v_exp_f32_e32 v93, v93
	v_rcp_f32_e32 v112, v112
	v_rcp_f32_e32 v113, v113
	v_rcp_f32_e32 v104, v104
	v_rcp_f32_e32 v105, v105
	v_lshl_or_b32 v152, s1, 7, v147
	v_pk_mul_f32 v[116:117], v[118:119], v[116:117]
	v_ashrrev_i32_e32 v153, 31, v152
	v_cvt_pk_bf16_f32 v127, v116, v117
	v_mov_b64_e32 v[116:117], s[8:9]
	v_mad_i64_i32 v[120:121], s[0:1], v151, s42, v[116:117]
	v_lshlrev_b64 v[118:119], 1, v[152:153]
	v_pk_add_f32 v[92:93], v[92:93], 1.0 op_sel_hi:[1,0]
	v_lshl_add_u64 v[120:121], v[120:121], 0, v[118:119]
	v_pk_mul_f32 v[110:111], v[110:111], v[112:113]
	v_pk_mul_f32 v[100:101], v[100:101], v[104:105]
	v_rcp_f32_e32 v92, v92
	v_rcp_f32_e32 v93, v93
	global_store_dwordx4 v[120:121], v[124:127], off
	v_cvt_pk_bf16_f32 v108, v108, v109
	v_cvt_pk_bf16_f32 v109, v110, v111
	v_cvt_pk_bf16_f32 v110, v100, v101
	v_pk_mul_f32 v[100:101], v[106:107], v[148:149] op_sel_hi:[1,0]
	v_pk_mul_f32 v[102:103], v[102:103], v[148:149] op_sel_hi:[1,0]
	v_pk_mul_f32 v[88:89], v[88:89], v[92:93]
	v_pk_mul_f32 v[102:103], v[100:101], v[102:103]
	v_pk_mul_f32 v[100:101], v[100:101], s[68:69] op_sel_hi:[1,0]
	v_pk_mul_f32 v[92:93], v[94:95], v[146:147] op_sel_hi:[1,0]
	v_exp_f32_e32 v100, v100
	v_exp_f32_e32 v101, v101
	v_pk_mul_f32 v[90:91], v[90:91], v[146:147] op_sel_hi:[1,0]
	v_pk_mul_f32 v[84:85], v[84:85], v[146:147] op_sel_hi:[1,0]
	v_pk_mul_f32 v[80:81], v[80:81], v[146:147] op_sel_hi:[1,0]
	v_pk_mul_f32 v[90:91], v[92:93], v[90:91]
	v_pk_mul_f32 v[92:93], v[92:93], s[68:69] op_sel_hi:[1,0]
	v_pk_mul_f32 v[80:81], v[84:85], v[80:81]
	v_pk_mul_f32 v[84:85], v[84:85], s[68:69] op_sel_hi:[1,0]
	v_exp_f32_e32 v92, v92
	v_exp_f32_e32 v93, v93
	v_exp_f32_e32 v84, v84
	v_exp_f32_e32 v85, v85
	v_pk_add_f32 v[100:101], v[100:101], 1.0 op_sel_hi:[1,0]
	v_pk_mul_f32 v[76:77], v[76:77], v[144:145] op_sel_hi:[1,0]
	v_rcp_f32_e32 v100, v100
	v_rcp_f32_e32 v101, v101
	v_pk_mul_f32 v[72:73], v[72:73], v[144:145] op_sel_hi:[1,0]
	v_pk_add_f32 v[92:93], v[92:93], 1.0 op_sel_hi:[1,0]
	v_pk_mul_f32 v[72:73], v[72:73], v[76:77]
	v_pk_mul_f32 v[76:77], v[76:77], s[68:69] op_sel_hi:[1,0]
	v_pk_add_f32 v[84:85], v[84:85], 1.0 op_sel_hi:[1,0]
	v_exp_f32_e32 v76, v76
	v_exp_f32_e32 v77, v77
	v_rcp_f32_e32 v92, v92
	v_rcp_f32_e32 v93, v93
	v_rcp_f32_e32 v84, v84
	v_rcp_f32_e32 v85, v85
	v_pk_mul_f32 v[100:101], v[102:103], v[100:101]
	v_pk_add_f32 v[76:77], v[76:77], 1.0 op_sel_hi:[1,0]
	v_cvt_pk_bf16_f32 v111, v100, v101
	v_or_b32_e32 v100, 16, v151
	v_mad_i64_i32 v[100:101], s[0:1], v100, s42, v[116:117]
	v_lshl_add_u64 v[100:101], v[100:101], 0, v[118:119]
	v_pk_mul_f32 v[90:91], v[90:91], v[92:93]
	v_pk_mul_f32 v[80:81], v[80:81], v[84:85]
	v_rcp_f32_e32 v76, v76
	v_rcp_f32_e32 v77, v77
	global_store_dwordx4 v[100:101], v[108:111], off
	v_cvt_pk_bf16_f32 v88, v88, v89
	v_cvt_pk_bf16_f32 v89, v90, v91
	v_cvt_pk_bf16_f32 v90, v80, v81
	v_pk_mul_f32 v[80:81], v[86:87], v[146:147] op_sel_hi:[1,0]
	v_pk_mul_f32 v[82:83], v[82:83], v[146:147] op_sel_hi:[1,0]
	v_pk_mul_f32 v[72:73], v[72:73], v[76:77]
	v_pk_mul_f32 v[82:83], v[80:81], v[82:83]
	v_pk_mul_f32 v[80:81], v[80:81], s[68:69] op_sel_hi:[1,0]
	v_pk_mul_f32 v[76:77], v[78:79], v[144:145] op_sel_hi:[1,0]
	v_exp_f32_e32 v80, v80
	v_exp_f32_e32 v81, v81
	v_pk_mul_f32 v[74:75], v[74:75], v[144:145] op_sel_hi:[1,0]
	v_pk_mul_f32 v[68:69], v[68:69], v[144:145] op_sel_hi:[1,0]
	v_pk_mul_f32 v[64:65], v[64:65], v[144:145] op_sel_hi:[1,0]
	v_pk_mul_f32 v[74:75], v[76:77], v[74:75]
	v_pk_mul_f32 v[76:77], v[76:77], s[68:69] op_sel_hi:[1,0]
	v_pk_mul_f32 v[64:65], v[68:69], v[64:65]
	v_pk_mul_f32 v[68:69], v[68:69], s[68:69] op_sel_hi:[1,0]
	v_exp_f32_e32 v76, v76
	v_exp_f32_e32 v77, v77
	v_exp_f32_e32 v68, v68
	v_exp_f32_e32 v69, v69
	v_pk_add_f32 v[80:81], v[80:81], 1.0 op_sel_hi:[1,0]
	v_pk_add_f32 v[76:77], v[76:77], 1.0 op_sel_hi:[1,0]
	v_rcp_f32_e32 v80, v80
	v_rcp_f32_e32 v81, v81
	v_pk_add_f32 v[68:69], v[68:69], 1.0 op_sel_hi:[1,0]
	v_rcp_f32_e32 v76, v76
	v_rcp_f32_e32 v77, v77
	v_rcp_f32_e32 v68, v68
	v_rcp_f32_e32 v69, v69
	v_pk_mul_f32 v[80:81], v[82:83], v[80:81]
	v_pk_mul_f32 v[74:75], v[74:75], v[76:77]
	v_cvt_pk_bf16_f32 v91, v80, v81
	v_or_b32_e32 v80, 32, v151
	v_mad_i64_i32 v[80:81], s[0:1], v80, s42, v[116:117]
	v_lshl_add_u64 v[80:81], v[80:81], 0, v[118:119]
	v_pk_mul_f32 v[64:65], v[64:65], v[68:69]
	global_store_dwordx4 v[80:81], v[88:91], off
	v_cvt_pk_bf16_f32 v72, v72, v73
	v_cvt_pk_bf16_f32 v73, v74, v75
	v_cvt_pk_bf16_f32 v74, v64, v65
	v_pk_mul_f32 v[64:65], v[70:71], v[144:145] op_sel_hi:[1,0]
	v_pk_mul_f32 v[66:67], v[66:67], v[144:145] op_sel_hi:[1,0]
	s_nop 0
	v_pk_mul_f32 v[66:67], v[64:65], v[66:67]
	v_pk_mul_f32 v[64:65], v[64:65], s[68:69] op_sel_hi:[1,0]
	s_nop 0
	v_exp_f32_e32 v64, v64
	v_exp_f32_e32 v65, v65
	s_nop 0
	v_pk_add_f32 v[64:65], v[64:65], 1.0 op_sel_hi:[1,0]
	s_nop 0
	v_rcp_f32_e32 v64, v64
	v_rcp_f32_e32 v65, v65
	s_nop 0
	v_pk_mul_f32 v[64:65], v[66:67], v[64:65]
	s_nop 0
	v_cvt_pk_bf16_f32 v75, v64, v65
	v_or_b32_e32 v64, 48, v151
	v_mad_i64_i32 v[64:65], s[0:1], v64, s42, v[116:117]
	v_lshl_add_u64 v[64:65], v[64:65], 0, v[118:119]
	global_store_dwordx4 v[64:65], v[72:75], off
	v_add_u32_e32 v64, 0x80, v151
	s_and_b64 vcc, exec, s[14:15]
	s_cbranch_vccz .Lsw_noalign
	s_barrier
.Lsw_noalign:
	v_pk_mul_f32 v[60:61], v[60:61], v[142:143] op_sel_hi:[1,0]
	v_pk_mul_f32 v[56:57], v[56:57], v[142:143] op_sel_hi:[1,0]
	v_pk_mul_f32 v[58:59], v[58:59], v[142:143] op_sel_hi:[1,0]
	v_pk_mul_f32 v[56:57], v[60:61], v[56:57]
	v_pk_mul_f32 v[60:61], v[60:61], s[68:69] op_sel_hi:[1,0]
	v_pk_mul_f32 v[52:53], v[52:53], v[142:143] op_sel_hi:[1,0]
	v_exp_f32_e32 v60, v60
	v_exp_f32_e32 v61, v61
	v_pk_mul_f32 v[48:49], v[48:49], v[142:143] op_sel_hi:[1,0]
	v_pk_mul_f32 v[44:45], v[44:45], v[140:141] op_sel_hi:[1,0]
	v_pk_mul_f32 v[48:49], v[52:53], v[48:49]
	v_pk_add_f32 v[60:61], v[60:61], 1.0 op_sel_hi:[1,0]
	v_pk_mul_f32 v[52:53], v[52:53], s[68:69] op_sel_hi:[1,0]
	v_rcp_f32_e32 v60, v60
	v_rcp_f32_e32 v61, v61
	v_exp_f32_e32 v52, v52
	v_exp_f32_e32 v53, v53
	v_pk_mul_f32 v[40:41], v[40:41], v[140:141] op_sel_hi:[1,0]
	v_pk_mul_f32 v[56:57], v[56:57], v[60:61]
	v_pk_mul_f32 v[60:61], v[62:63], v[142:143] op_sel_hi:[1,0]
	v_pk_mul_f32 v[40:41], v[40:41], v[44:45]
	v_pk_mul_f32 v[58:59], v[60:61], v[58:59]
	v_pk_mul_f32 v[60:61], v[60:61], s[68:69] op_sel_hi:[1,0]
	v_pk_mul_f32 v[44:45], v[44:45], s[68:69] op_sel_hi:[1,0]
	v_exp_f32_e32 v60, v60
	v_exp_f32_e32 v61, v61
	v_exp_f32_e32 v44, v44
	v_exp_f32_e32 v45, v45
	v_pk_add_f32 v[52:53], v[52:53], 1.0 op_sel_hi:[1,0]
	v_pk_add_f32 v[60:61], v[60:61], 1.0 op_sel_hi:[1,0]
	v_rcp_f32_e32 v52, v52
	v_rcp_f32_e32 v60, v60
	v_rcp_f32_e32 v61, v61
	v_rcp_f32_e32 v53, v53
	v_pk_add_f32 v[44:45], v[44:45], 1.0 op_sel_hi:[1,0]
	v_cvt_pk_bf16_f32 v56, v56, v57
	v_pk_mul_f32 v[58:59], v[58:59], v[60:61]
	v_rcp_f32_e32 v44, v44
	v_rcp_f32_e32 v45, v45
	v_pk_mul_f32 v[48:49], v[48:49], v[52:53]
	v_cvt_pk_bf16_f32 v57, v58, v59
	v_pk_mul_f32 v[50:51], v[50:51], v[142:143] op_sel_hi:[1,0]
	v_cvt_pk_bf16_f32 v58, v48, v49
	v_pk_mul_f32 v[48:49], v[54:55], v[142:143] op_sel_hi:[1,0]
	v_pk_mul_f32 v[40:41], v[40:41], v[44:45]
	v_pk_mul_f32 v[50:51], v[48:49], v[50:51]
	v_pk_mul_f32 v[48:49], v[48:49], s[68:69] op_sel_hi:[1,0]
	v_pk_mul_f32 v[44:45], v[46:47], v[140:141] op_sel_hi:[1,0]
	v_exp_f32_e32 v48, v48
	v_exp_f32_e32 v49, v49
	v_pk_mul_f32 v[42:43], v[42:43], v[140:141] op_sel_hi:[1,0]
	v_pk_mul_f32 v[36:37], v[36:37], v[140:141] op_sel_hi:[1,0]
	v_pk_mul_f32 v[32:33], v[32:33], v[140:141] op_sel_hi:[1,0]
	v_pk_mul_f32 v[42:43], v[44:45], v[42:43]
	v_pk_mul_f32 v[44:45], v[44:45], s[68:69] op_sel_hi:[1,0]
	v_pk_mul_f32 v[32:33], v[36:37], v[32:33]
	v_pk_mul_f32 v[36:37], v[36:37], s[68:69] op_sel_hi:[1,0]
	v_exp_f32_e32 v44, v44
	v_exp_f32_e32 v45, v45
	v_exp_f32_e32 v36, v36
	v_exp_f32_e32 v37, v37
	v_pk_add_f32 v[48:49], v[48:49], 1.0 op_sel_hi:[1,0]
	v_pk_mul_f32 v[28:29], v[28:29], v[138:139] op_sel_hi:[1,0]
	v_pk_mul_f32 v[24:25], v[24:25], v[138:139] op_sel_hi:[1,0]
	v_rcp_f32_e32 v48, v48
	v_rcp_f32_e32 v49, v49
	v_pk_mul_f32 v[24:25], v[24:25], v[28:29]
	v_pk_mul_f32 v[28:29], v[28:29], s[68:69] op_sel_hi:[1,0]
	v_pk_add_f32 v[44:45], v[44:45], 1.0 op_sel_hi:[1,0]
	v_pk_add_f32 v[36:37], v[36:37], 1.0 op_sel_hi:[1,0]
	v_exp_f32_e32 v28, v28
	v_exp_f32_e32 v29, v29
	v_rcp_f32_e32 v44, v44
	v_rcp_f32_e32 v45, v45
	v_rcp_f32_e32 v36, v36
	v_rcp_f32_e32 v37, v37
	v_pk_mul_f32 v[48:49], v[50:51], v[48:49]
	v_pk_add_f32 v[28:29], v[28:29], 1.0 op_sel_hi:[1,0]
	v_cvt_pk_bf16_f32 v59, v48, v49
	v_mad_i64_i32 v[48:49], s[0:1], v64, s42, v[116:117]
	v_lshl_add_u64 v[48:49], v[48:49], 0, v[118:119]
	v_pk_mul_f32 v[42:43], v[42:43], v[44:45]
	v_pk_mul_f32 v[32:33], v[32:33], v[36:37]
	v_rcp_f32_e32 v28, v28
	v_rcp_f32_e32 v29, v29
	global_store_dwordx4 v[48:49], v[56:59], off
	v_cvt_pk_bf16_f32 v40, v40, v41
	v_cvt_pk_bf16_f32 v41, v42, v43
	v_cvt_pk_bf16_f32 v42, v32, v33
	v_pk_mul_f32 v[32:33], v[38:39], v[140:141] op_sel_hi:[1,0]
	v_pk_mul_f32 v[34:35], v[34:35], v[140:141] op_sel_hi:[1,0]
	v_pk_mul_f32 v[24:25], v[24:25], v[28:29]
	v_pk_mul_f32 v[34:35], v[32:33], v[34:35]
	v_pk_mul_f32 v[32:33], v[32:33], s[68:69] op_sel_hi:[1,0]
	v_pk_mul_f32 v[28:29], v[30:31], v[138:139] op_sel_hi:[1,0]
	v_exp_f32_e32 v32, v32
	v_exp_f32_e32 v33, v33
	v_pk_mul_f32 v[26:27], v[26:27], v[138:139] op_sel_hi:[1,0]
	v_pk_mul_f32 v[20:21], v[20:21], v[138:139] op_sel_hi:[1,0]
	v_pk_mul_f32 v[16:17], v[16:17], v[138:139] op_sel_hi:[1,0]
	v_pk_mul_f32 v[26:27], v[28:29], v[26:27]
	v_pk_mul_f32 v[28:29], v[28:29], s[68:69] op_sel_hi:[1,0]
	v_pk_mul_f32 v[16:17], v[20:21], v[16:17]
	v_pk_mul_f32 v[20:21], v[20:21], s[68:69] op_sel_hi:[1,0]
	v_exp_f32_e32 v28, v28
	v_exp_f32_e32 v29, v29
	v_exp_f32_e32 v20, v20
	v_exp_f32_e32 v21, v21
	v_pk_add_f32 v[32:33], v[32:33], 1.0 op_sel_hi:[1,0]
	v_pk_add_f32 v[28:29], v[28:29], 1.0 op_sel_hi:[1,0]
	v_rcp_f32_e32 v32, v32
	v_rcp_f32_e32 v33, v33
	v_pk_add_f32 v[20:21], v[20:21], 1.0 op_sel_hi:[1,0]
	v_rcp_f32_e32 v28, v28
	v_rcp_f32_e32 v29, v29
	v_rcp_f32_e32 v20, v20
	v_rcp_f32_e32 v21, v21
	v_pk_mul_f32 v[32:33], v[34:35], v[32:33]
	v_pk_mul_f32 v[26:27], v[26:27], v[28:29]
	v_cvt_pk_bf16_f32 v43, v32, v33
	v_add_u32_e32 v32, 0x90, v151
	v_mad_i64_i32 v[32:33], s[0:1], v32, s42, v[116:117]
	v_lshl_add_u64 v[32:33], v[32:33], 0, v[118:119]
	v_pk_mul_f32 v[16:17], v[16:17], v[20:21]
	global_store_dwordx4 v[32:33], v[40:43], off
	v_cvt_pk_bf16_f32 v24, v24, v25
	v_cvt_pk_bf16_f32 v25, v26, v27
	v_cvt_pk_bf16_f32 v26, v16, v17
	v_pk_mul_f32 v[16:17], v[22:23], v[138:139] op_sel_hi:[1,0]
	v_pk_mul_f32 v[18:19], v[18:19], v[138:139] op_sel_hi:[1,0]
	s_mov_b64 s[24:25], -1
	v_pk_mul_f32 v[18:19], v[16:17], v[18:19]
	v_pk_mul_f32 v[16:17], v[16:17], s[68:69] op_sel_hi:[1,0]
	s_andn2_b64 vcc, exec, s[4:5]
	v_exp_f32_e32 v16, v16
	v_exp_f32_e32 v17, v17
	s_nop 0
	v_pk_add_f32 v[16:17], v[16:17], 1.0 op_sel_hi:[1,0]
	s_nop 0
	v_rcp_f32_e32 v16, v16
	v_rcp_f32_e32 v17, v17
	s_nop 0
	v_pk_mul_f32 v[16:17], v[18:19], v[16:17]
	s_nop 0
	v_cvt_pk_bf16_f32 v27, v16, v17
	v_add_u32_e32 v16, 0xa0, v151
	v_mad_i64_i32 v[16:17], s[0:1], v16, s42, v[116:117]
	v_lshl_add_u64 v[16:17], v[16:17], 0, v[118:119]
	global_store_dwordx4 v[16:17], v[24:27], off
	s_waitcnt lgkmcnt(0)
	v_mov_b32_e32 v16, v235
	v_mov_b32_e32 v17, v236
	v_mov_b32_e32 v235, v237
	v_pk_add_f32 v[16:17], v[16:17], v[234:235]
	s_nop 0
	v_add_f32_e32 v16, v16, v17
	v_fmamk_f32 v16, v16, 0x3a800000, v229
	v_rsq_f32_e32 v16, v16
	s_nop 0
	v_pk_mul_f32 v[12:13], v[12:13], v[16:17] op_sel_hi:[1,0]
	v_pk_mul_f32 v[8:9], v[8:9], v[16:17] op_sel_hi:[1,0]
	v_pk_mul_f32 v[10:11], v[10:11], v[16:17] op_sel_hi:[1,0]
	v_pk_mul_f32 v[8:9], v[8:9], v[12:13]
	v_pk_mul_f32 v[12:13], v[12:13], s[68:69] op_sel_hi:[1,0]
	v_pk_mul_f32 v[4:5], v[4:5], v[16:17] op_sel_hi:[1,0]
	v_exp_f32_e32 v12, v12
	v_exp_f32_e32 v13, v13
	v_pk_mul_f32 v[0:1], v[0:1], v[16:17] op_sel_hi:[1,0]
	v_pk_mul_f32 v[2:3], v[2:3], v[16:17] op_sel_hi:[1,0]
	v_pk_mul_f32 v[0:1], v[4:5], v[0:1]
	v_pk_add_f32 v[12:13], v[12:13], 1.0 op_sel_hi:[1,0]
	v_pk_mul_f32 v[4:5], v[4:5], s[68:69] op_sel_hi:[1,0]
	v_rcp_f32_e32 v12, v12
	v_rcp_f32_e32 v13, v13
	v_exp_f32_e32 v4, v4
	v_exp_f32_e32 v5, v5
	v_pk_mul_f32 v[8:9], v[8:9], v[12:13]
	v_pk_mul_f32 v[12:13], v[14:15], v[16:17] op_sel_hi:[1,0]
	v_pk_add_f32 v[4:5], v[4:5], 1.0 op_sel_hi:[1,0]
	v_pk_mul_f32 v[10:11], v[12:13], v[10:11]
	v_pk_mul_f32 v[12:13], v[12:13], s[68:69] op_sel_hi:[1,0]
	v_rcp_f32_e32 v4, v4
	v_exp_f32_e32 v12, v12
	v_exp_f32_e32 v13, v13
	v_rcp_f32_e32 v5, v5
	v_cvt_pk_bf16_f32 v8, v8, v9
	v_pk_add_f32 v[12:13], v[12:13], 1.0 op_sel_hi:[1,0]
	s_nop 0
	v_rcp_f32_e32 v12, v12
	v_rcp_f32_e32 v13, v13
	v_pk_mul_f32 v[0:1], v[0:1], v[4:5]
	v_pk_mul_f32 v[10:11], v[10:11], v[12:13]
	s_nop 0
	v_cvt_pk_bf16_f32 v9, v10, v11
	v_cvt_pk_bf16_f32 v10, v0, v1
	v_pk_mul_f32 v[0:1], v[6:7], v[16:17] op_sel_hi:[1,0]
	s_nop 0
	v_pk_mul_f32 v[2:3], v[0:1], v[2:3]
	v_pk_mul_f32 v[0:1], v[0:1], s[68:69] op_sel_hi:[1,0]
	s_nop 0
	v_exp_f32_e32 v0, v0
	v_exp_f32_e32 v1, v1
	s_nop 0
	v_pk_add_f32 v[0:1], v[0:1], 1.0 op_sel_hi:[1,0]
	s_nop 0
	v_rcp_f32_e32 v0, v0
	v_rcp_f32_e32 v1, v1
	s_nop 0
	v_pk_mul_f32 v[0:1], v[2:3], v[0:1]
	s_nop 0
	v_cvt_pk_bf16_f32 v11, v0, v1
	v_add_u32_e32 v0, 0xb0, v151
	v_mad_i64_i32 v[0:1], s[0:1], v0, s42, v[116:117]
	v_lshl_add_u64 v[0:1], v[0:1], 0, v[118:119]
	global_store_dwordx4 v[0:1], v[8:11], off
	s_cbranch_vccnz .LBB0_522
	s_andn2_b64 vcc, exec, s[6:7]
	s_cbranch_vccnz .LBB0_521
	s_barrier
	s_branch .LBB0_521
